# prep loads issued together; normmod loads hoisted + DPP wave reduce; final gain loads hoisted
# speedup vs baseline: 1.0414x; 1.0161x over previous
; __device__ __forceinline__ unsigned pk2(float lo, float hi) { unsigned r; asm("v_cvt_pk_bf16_f32 %0, %1, %2" : "=v"(r) : "v"(lo), "v"(hi)); return r; }
; __device__ __forceinline__ float wave_sum(float v) {
; #pragma unroll
;     for (int o = 1; o < 64; o <<= 1) v += __shfl_xor(v, o);
;     return v;
; }
; __device__ __forceinline__ void ph_normmod(const P& p, const float* srclat, const float* srcctx, int rows, int l, int idx, int gw, int ngw, int lane) {
;     ...
;     for (int m = gw; m < rows; m += ngw) {
;         const float* src = m < MLAT ? srclat + (size_t)m * DM : srcctx + (size_t)(m - MLAT) * DM;
;         const int mr = m < MLAT ? (m >> 11) : 8;
;         const float* sh = mod + mr * 9216 + (3 * idx) * DM; const float* sc = sh + DM;
;         f32x4 v[4]; float ss = 0.f;
; #pragma unroll
;         for (int j = 0; j < 4; ++j) { v[j] = *(const f32x4*)(src + 4 * lane + 256 * j); ss += v[j][0] * v[j][0] + v[j][1] * v[j][1] + v[j][2] * v[j][2] + v[j][3] * v[j][3]; }
;         const float rstd = 1.0f / sqrtf(wave_sum(ss) * (1.f / DM) + EPS);
; #pragma unroll
;         for (int j = 0; j < 4; ++j) { const int col = 4 * lane + 256 * j;
;             const f32x4 gv = *(const f32x4*)(g + col), shv = *(const f32x4*)(sh + col), scv = *(const f32x4*)(sc + col);
;             const f32x4 o = v[j] * rstd * gv * (scv + 1.0f) + shv;
;             u32x2 w; w.x = pk2(o[0], o[1]); w.y = pk2(o[2], o[3]); *(u32x2*)(A + (size_t)m * DM + col) = w; }
;     }
.LBB0_101:
	global_load_dwordx4 v[24:27], v0, s[10:11]
	global_load_dwordx4 v[28:31], v0, s[10:11] offset:1024
	global_load_dwordx4 v[6:9], v0, s[10:11] offset:2048
	global_load_dwordx4 v[2:5], v0, s[10:11] offset:3072
	s_min_i32 s10, s2, 0x4000
	s_ashr_i32 s10, s10, 11
	s_mulk_i32 s10, 0x2400
	s_ashr_i32 s11, s10, 31
	s_lshl_b64 s[10:11], s[10:11], 2
	s_add_u32 s10, s16, s10
	s_addc_u32 s11, s17, s11
	s_add_u32 s12, s10, 0x1000
	s_addc_u32 s13, s11, 0
	global_load_dwordx4 v[36:39], v[10:11], off
	global_load_dwordx4 v[88:91], v[10:11], off offset:1024
	global_load_dwordx4 v[100:103], v[10:11], off offset:2048
	global_load_dwordx4 v[112:115], v[10:11], off offset:3072
	global_load_dwordx4 v[32:35], v0, s[12:13]
	global_load_dwordx4 v[92:95], v0, s[12:13] offset:1024
	global_load_dwordx4 v[104:107], v0, s[12:13] offset:2048
	global_load_dwordx4 v[116:119], v0, s[12:13] offset:3072
	global_load_dwordx4 v[40:43], v0, s[10:11]
	global_load_dwordx4 v[96:99], v0, s[10:11] offset:1024
	global_load_dwordx4 v[108:111], v0, s[10:11] offset:2048
	global_load_dwordx4 v[120:123], v0, s[10:11] offset:3072
	s_lshl_b64 s[6:7], s[6:7], 11
	s_add_u32 s2, s2, s4
	s_addc_u32 s3, s3, s5
	s_add_u32 s8, s8, s78
	s_addc_u32 s9, s9, s79
	s_cmp_lt_i32 s2, s42
	s_waitcnt vmcnt(15)
	v_mul_f32_e32 v23, v25, v25
	s_waitcnt vmcnt(14)
	v_mul_f32_e32 v52, v29, v29
	s_waitcnt vmcnt(13)
	v_mov_b32_e32 v46, v7
	s_waitcnt vmcnt(12)
	v_mov_b32_e32 v47, v3
	v_mov_b32_e32 v44, v6
	v_mov_b32_e32 v45, v2
	v_fmac_f32_e32 v23, v24, v24
	v_fmac_f32_e32 v52, v28, v28
	v_pk_mul_f32 v[46:47], v[46:47], v[46:47]
	v_mov_b32_e32 v48, v8
	v_mov_b32_e32 v49, v4
	v_fmac_f32_e32 v23, v26, v26
	v_fmac_f32_e32 v52, v30, v30
	v_pk_fma_f32 v[44:45], v[44:45], v[44:45], v[46:47]
	v_mov_b32_e32 v50, v9
	v_mov_b32_e32 v51, v5
	v_fmac_f32_e32 v23, v27, v27
	v_fmac_f32_e32 v52, v31, v31
	v_pk_fma_f32 v[44:45], v[48:49], v[48:49], v[44:45]
	v_add_f32_e32 v23, v23, v52
	v_pk_fma_f32 v[44:45], v[50:51], v[50:51], v[44:45]
	s_nop 0
	v_add_f32_e32 v23, v23, v44
	v_add_f32_e32 v23, v23, v45
	s_nop 1
	v_add_f32_dpp v23, v23, v23 quad_perm:[1,0,3,2] row_mask:0xf bank_mask:0xf
	s_nop 1
	v_add_f32_dpp v23, v23, v23 quad_perm:[2,3,0,1] row_mask:0xf bank_mask:0xf
	s_nop 1
	v_add_f32_dpp v23, v23, v23 row_half_mirror row_mask:0xf bank_mask:0xf
	s_nop 1
	v_add_f32_dpp v23, v23, v23 row_mirror row_mask:0xf bank_mask:0xf
	s_nop 1
	v_readlane_b32 s24, v23, 0
	v_readlane_b32 s25, v23, 16
	v_readlane_b32 s26, v23, 32
	v_readlane_b32 s27, v23, 48
	s_nop 1
	v_mov_b32_e32 v23, s24
	v_add_f32_e32 v23, s25, v23
	v_add_f32_e32 v23, s26, v23
	v_add_f32_e32 v23, s27, v23
	v_fmamk_f32 v23, v23, 0x3a800000, v194
	v_mul_f32_e32 v44, 0x4f800000, v23
	v_cmp_gt_f32_e32 vcc, s53, v23
	s_nop 1
	v_cndmask_b32_e32 v23, v23, v44, vcc
	v_sqrt_f32_e32 v46, v23
	v_lshl_add_u64 v[44:45], v[12:13], 0, s[6:7]
	v_add_u32_e32 v47, -1, v46
	v_add_u32_e32 v48, 1, v46
	v_fma_f32 v49, -v47, v46, v23
	v_fma_f32 v50, -v48, v46, v23
	v_cmp_ge_f32_e64 s[6:7], 0, v49
	s_nop 1
	v_cndmask_b32_e64 v46, v46, v47, s[6:7]
	v_cmp_lt_f32_e64 s[6:7], 0, v50
	s_nop 1
	v_cndmask_b32_e64 v46, v46, v48, s[6:7]
	v_mul_f32_e32 v47, 0x37800000, v46
	v_cndmask_b32_e32 v46, v46, v47, vcc
	v_cmp_class_f32_e32 vcc, v23, v195
	s_nop 1
	v_cndmask_b32_e32 v23, v46, v23, vcc
	v_div_scale_f32 v46, s[6:7], v23, v23, 1.0
	v_rcp_f32_e32 v47, v46
	v_div_scale_f32 v48, vcc, 1.0, v23, 1.0
	v_fma_f32 v49, -v46, v47, 1.0
	v_fmac_f32_e32 v47, v49, v47
	v_mul_f32_e32 v49, v48, v47
	v_fma_f32 v50, -v46, v49, v48
	v_fmac_f32_e32 v49, v50, v47
	v_fma_f32 v46, -v46, v49, v48
	v_div_fmas_f32 v46, v46, v47, v49
	v_div_fixup_f32 v46, v46, v23, 1.0
	v_pk_mul_f32 v[24:25], v[24:25], v[46:47] op_sel_hi:[1,0]
	v_pk_mul_f32 v[26:27], v[26:27], v[46:47] op_sel_hi:[1,0]
	v_pk_mul_f32 v[28:29], v[28:29], v[46:47] op_sel_hi:[1,0]
	v_pk_mul_f32 v[30:31], v[30:31], v[46:47] op_sel_hi:[1,0]
	v_pk_mul_f32 v[6:7], v[6:7], v[46:47] op_sel_hi:[1,0]
	v_pk_mul_f32 v[8:9], v[8:9], v[46:47] op_sel_hi:[1,0]
	v_pk_mul_f32 v[2:3], v[2:3], v[46:47] op_sel_hi:[1,0]
	v_pk_mul_f32 v[4:5], v[4:5], v[46:47] op_sel_hi:[1,0]
	s_waitcnt vmcnt(8)
	v_pk_mul_f32 v[24:25], v[36:37], v[24:25]
	v_pk_mul_f32 v[26:27], v[38:39], v[26:27]
	v_pk_mul_f32 v[28:29], v[88:89], v[28:29]
	v_pk_mul_f32 v[30:31], v[90:91], v[30:31]
	v_pk_mul_f32 v[6:7], v[6:7], v[100:101]
	v_pk_mul_f32 v[8:9], v[8:9], v[102:103]
	v_pk_mul_f32 v[2:3], v[2:3], v[112:113]
	v_pk_mul_f32 v[4:5], v[4:5], v[114:115]
	s_waitcnt vmcnt(4)
	v_pk_add_f32 v[32:33], v[32:33], 1.0 op_sel_hi:[1,0]
	v_pk_add_f32 v[34:35], v[34:35], 1.0 op_sel_hi:[1,0]
	v_pk_add_f32 v[92:93], v[92:93], 1.0 op_sel_hi:[1,0]
	v_pk_add_f32 v[94:95], v[94:95], 1.0 op_sel_hi:[1,0]
	v_pk_add_f32 v[104:105], v[104:105], 1.0 op_sel_hi:[1,0]
	v_pk_add_f32 v[106:107], v[106:107], 1.0 op_sel_hi:[1,0]
	v_pk_add_f32 v[116:117], v[116:117], 1.0 op_sel_hi:[1,0]
	v_pk_add_f32 v[118:119], v[118:119], 1.0 op_sel_hi:[1,0]
	s_waitcnt vmcnt(0)
	v_pk_fma_f32 v[24:25], v[32:33], v[24:25], v[40:41]
	v_pk_fma_f32 v[26:27], v[34:35], v[26:27], v[42:43]
	v_pk_fma_f32 v[28:29], v[92:93], v[28:29], v[96:97]
	v_pk_fma_f32 v[30:31], v[94:95], v[30:31], v[98:99]
	v_pk_fma_f32 v[6:7], v[6:7], v[104:105], v[108:109]
	v_pk_fma_f32 v[8:9], v[8:9], v[106:107], v[110:111]
	v_pk_fma_f32 v[2:3], v[2:3], v[116:117], v[120:121]
	v_pk_fma_f32 v[4:5], v[4:5], v[118:119], v[122:123]
	v_cvt_pk_bf16_f32 v24, v24, v25
	v_cvt_pk_bf16_f32 v25, v26, v27
	v_cvt_pk_bf16_f32 v28, v28, v29
	v_cvt_pk_bf16_f32 v29, v30, v31
	v_cvt_pk_bf16_f32 v6, v6, v7
	v_cvt_pk_bf16_f32 v7, v8, v9
	v_cvt_pk_bf16_f32 v2, v2, v3
	v_cvt_pk_bf16_f32 v3, v4, v5
	global_store_dwordx2 v[44:45], v[24:25], off
	global_store_dwordx2 v[44:45], v[28:29], off offset:512
	global_store_dwordx2 v[44:45], v[6:7], off offset:1024
	global_store_dwordx2 v[44:45], v[2:3], off offset:1536
	s_cbranch_scc0 .LBB0_104

; __device__ __forceinline__ f32x4 mfma16(bf16x8 a, bf16x8 b, f32x4 c) { return __builtin_amdgcn_mfma_f32_16x16x32_bf16(a, b, c, 0, 0, 0); }
; __device__ __forceinline__ void dn_prep_task(const P& p, int task, unsigned char* sm, int tid) {
;     ...
;     {
;         const int r = tid >> 3, c16 = (tid & 7) * 16;
;         const bf16_t* ks = (const bf16_t*)(p.ws + WS_KN) + (size_t)(m0 + r) * 512 + h * 128 + c16;
;         const bf16_t* qs = (const bf16_t*)(p.ws + WS_QN) + (size_t)(m0 + r) * 512 + h * 128 + c16;
;         *(u32x4*)(kn_s + r * 136 + c16) = *(const u32x4*)ks; *(u32x4*)(kn_s + r * 136 + c16 + 8) = *(const u32x4*)(ks + 8);
;         *(u32x4*)(qn_s + r * 136 + c16) = *(const u32x4*)qs; *(u32x4*)(qn_s + r * 136 + c16 + 8) = *(const u32x4*)(qs + 8);
;         const bf16_t* vs = (const bf16_t*)(p.ws + WS_VV) + (size_t)(m0 + r) * 512 + h * 128 + c16;
;         *(u32x4*)(v_s + r * 136 + c16) = *(const u32x4*)vs; *(u32x4*)(v_s + r * 136 + c16 + 8) = *(const u32x4*)(vs + 8);
;     }
;     if (t2 < 64) {
;         const int tok = dir ? 63 - t2 : t2;
;         const float* gb = (const float*)(p.ws + WS_GB) + (size_t)(m0 + tok) * 16;
;         float gv = gb[dir * 4 + h]; const float bv = gb[8 + dir * 4 + h];
; #pragma unroll
;         for (int o = 1; o < 64; o <<= 1) { const float v = __shfl_up(gv, o); if (lane >= o) gv += v; }
;         gc_s[dir * 64 + t2] = gv; be_s[dir * 64 + t2] = bv;
;     }
;     __syncthreads();
;     {
;         const int which = wave >> 2, it = wave & 3, fr = lane & 15, g = lane >> 4;
;         const bf16_t* As = which ? qn_s : kn_s; float* Out = which ? QK : KK;
;         bf16x8 a[4];
; #pragma unroll
;         for (int ks = 0; ks < 4; ++ks) a[ks] = *(const bf16x8*)(As + (it * 16 + fr) * 136 + ks * 32 + g * 8);
; #pragma unroll
;         for (int jt = 0; jt < 4; ++jt) {
;             f32x4 acc = {0.f, 0.f, 0.f, 0.f};
; #pragma unroll
;             for (int ks = 0; ks < 4; ++ks) { const bf16x8 bb = *(const bf16x8*)(kn_s + (jt * 16 + fr) * 136 + ks * 32 + g * 8); acc = mfma16(a[ks], bb, acc); }
; #pragma unroll
;             for (int r = 0; r < 4; ++r) Out[(it * 16 + 4 * g + r) * 65 + jt * 16 + fr] = acc[r];
;         }
;     }
;     __syncthreads();
.LBB0_577:
	v_add_u32_e32 v2, s3, v9
	v_ashrrev_i32_e32 v3, 31, v2
	s_and_b32 s80, s2, 3
	v_lshlrev_b64 v[6:7], 10, v[2:3]
	v_lshl_add_u64 v[2:3], s[46:47], 0, v[6:7]
	s_lshl_b32 s64, s80, 8
	v_lshl_add_u64 v[2:3], v[2:3], 0, s[64:65]
	v_lshl_add_u64 v[26:27], v[2:3], 0, v[0:1]
	v_lshl_add_u64 v[2:3], s[48:49], 0, v[6:7]
	v_lshl_add_u64 v[2:3], v[2:3], 0, s[64:65]
	v_lshl_add_u64 v[30:31], v[2:3], 0, v[0:1]
	v_lshl_add_u64 v[2:3], s[28:29], 0, v[6:7]
	v_lshl_add_u64 v[2:3], v[2:3], 0, s[64:65]
	v_lshl_add_u64 v[50:51], v[2:3], 0, v[0:1]
	s_and_saveexec_b64 s[82:83], s[40:41]
	s_cbranch_execz .Lpl_a
	v_add_u32_e32 v2, s3, v91
	v_ashrrev_i32_e32 v3, 31, v2
	v_readlane_b32 s72, v255, 14
	v_lshlrev_b64 v[2:3], 6, v[2:3]
	v_readlane_b32 s73, v255, 15
	v_or_b32_e32 v4, s80, v10
	v_ashrrev_i32_e32 v5, 31, v4
	v_lshl_add_u64 v[2:3], s[72:73], 0, v[2:3]
	v_lshl_add_u64 v[4:5], v[4:5], 2, v[2:3]
	global_load_dword v6, v[4:5], off
	s_mov_b32 s81, s65
	v_lshl_add_u64 v[4:5], s[80:81], 0, v[10:11]
	v_lshl_add_u64 v[2:3], v[4:5], 2, v[2:3]
	global_load_dword v2, v[2:3], off offset:32
.Lpl_a:
	s_or_b64 exec, exec, s[82:83]
	global_load_dwordx4 v[34:37], v[26:27], off offset:16
	global_load_dwordx4 v[38:41], v[26:27], off
	global_load_dwordx4 v[42:45], v[30:31], off offset:16
	global_load_dwordx4 v[46:49], v[30:31], off
	global_load_dwordx4 v[52:55], v[50:51], off offset:16
	global_load_dwordx4 v[56:59], v[50:51], off
	s_and_saveexec_b64 s[82:83], s[40:41]
	s_cbranch_execz .Lpl_b
	v_add_u32_e32 v3, -1, v185
	v_cmp_lt_i32_e32 vcc, v3, v193
	v_add_u32_e32 v4, -2, v185
	v_readlane_b32 s72, v255, 16
	v_cndmask_b32_e32 v3, v3, v185, vcc
	v_lshlrev_b32_e32 v3, 2, v3
	v_cmp_lt_i32_e32 vcc, v4, v193
	v_readlane_b32 s73, v255, 17
	v_add_u32_e32 v5, -4, v185
	v_cndmask_b32_e32 v4, v4, v185, vcc
	v_lshlrev_b32_e32 v4, 2, v4
	v_cmp_lt_i32_e32 vcc, v5, v193
	s_waitcnt vmcnt(7)
	ds_bpermute_b32 v3, v3, v6
	v_cndmask_b32_e32 v5, v5, v185, vcc
	v_lshlrev_b32_e32 v5, 2, v5
	s_waitcnt lgkmcnt(0)
	v_add_f32_e32 v3, v6, v3
	v_cndmask_b32_e64 v3, v3, v6, s[72:73]
	ds_bpermute_b32 v4, v4, v3
	v_readlane_b32 s72, v255, 18
	v_readlane_b32 s73, v255, 19
	s_waitcnt lgkmcnt(0)
	v_add_f32_e32 v4, v3, v4
	v_cndmask_b32_e64 v3, v4, v3, s[72:73]
	ds_bpermute_b32 v4, v5, v3
	v_add_u32_e32 v5, -8, v185
	v_cmp_lt_i32_e32 vcc, v5, v193
	v_readlane_b32 s72, v255, 20
	v_readlane_b32 s73, v255, 21
	v_cndmask_b32_e32 v5, v5, v185, vcc
	s_waitcnt lgkmcnt(0)
	v_add_f32_e32 v4, v3, v4
	v_lshlrev_b32_e32 v5, 2, v5
	v_cndmask_b32_e64 v3, v4, v3, s[72:73]
	ds_bpermute_b32 v4, v5, v3
	v_add_u32_e32 v5, -16, v185
	v_cmp_lt_i32_e32 vcc, v5, v193
	v_readlane_b32 s72, v255, 22
	v_readlane_b32 s73, v255, 23
	v_cndmask_b32_e32 v5, v5, v185, vcc
	s_waitcnt lgkmcnt(0)
	v_add_f32_e32 v4, v3, v4
	v_lshlrev_b32_e32 v5, 2, v5
	v_cndmask_b32_e64 v3, v4, v3, s[72:73]
	ds_bpermute_b32 v4, v5, v3
	v_subrev_u32_e32 v5, 32, v185
	v_cmp_lt_i32_e32 vcc, v5, v193
	v_readlane_b32 s72, v255, 24
	v_readlane_b32 s73, v255, 25
	v_cndmask_b32_e32 v5, v5, v185, vcc
	s_waitcnt lgkmcnt(0)
	v_add_f32_e32 v4, v3, v4
	v_lshlrev_b32_e32 v5, 2, v5
	v_cndmask_b32_e64 v3, v4, v3, s[72:73]
	ds_bpermute_b32 v4, v5, v3
	v_readlane_b32 s72, v255, 26
	v_readlane_b32 s73, v255, 27
	s_waitcnt lgkmcnt(0)
	v_add_f32_e32 v4, v3, v4
	v_cndmask_b32_e64 v3, v4, v3, s[72:73]
	ds_write_b32 v92, v3
	s_waitcnt vmcnt(6)
	ds_write_b32 v93, v2
.Lpl_b:
	s_or_b64 exec, exec, s[82:83]
	s_waitcnt vmcnt(4)
	ds_write_b128 v89, v[38:41]
	ds_write_b128 v89, v[34:37] offset:16
	s_waitcnt vmcnt(2)
	ds_write_b128 v89, v[46:49] offset:17408
	ds_write_b128 v89, v[42:45] offset:17424
	s_waitcnt vmcnt(0)
	ds_write_b128 v90, v[56:59]
	ds_write_b128 v90, v[52:55] offset:16
	s_waitcnt lgkmcnt(0)
	s_barrier
	ds_read_b128 v[2:5], v148
	ds_read_b128 v[26:29], v148 offset:64
	ds_read_b128 v[30:33], v148 offset:128
	ds_read_b128 v[34:37], v148 offset:192
	ds_read_b128 v[38:41], v149
	ds_read_b128 v[42:45], v149 offset:64
	s_waitcnt lgkmcnt(1)
	v_mfma_f32_16x16x32_bf16 v[38:41], v[2:5], v[38:41], 0
	s_waitcnt lgkmcnt(0)
	v_mfma_f32_16x16x32_bf16 v[38:41], v[26:29], v[42:45], v[38:41]
	ds_read_b128 v[42:45], v149 offset:128
	s_waitcnt lgkmcnt(0)
	v_mfma_f32_16x16x32_bf16 v[38:41], v[30:33], v[42:45], v[38:41]
	ds_read_b128 v[42:45], v149 offset:192
	s_waitcnt lgkmcnt(0)
	v_mfma_f32_16x16x32_bf16 v[38:41], v[34:37], v[42:45], v[38:41]
	s_nop 7
	ds_write_b32 v150, v38
	ds_write_b32 v150, v39 offset:260
	ds_write_b32 v150, v40 offset:520
	ds_write_b32 v150, v41 offset:780
	ds_read_b128 v[38:41], v149 offset:4352
	ds_read_b128 v[42:45], v149 offset:4416
	s_waitcnt lgkmcnt(1)
	v_mfma_f32_16x16x32_bf16 v[38:41], v[2:5], v[38:41], 0
	s_waitcnt lgkmcnt(0)
	v_mfma_f32_16x16x32_bf16 v[38:41], v[26:29], v[42:45], v[38:41]
	ds_read_b128 v[42:45], v149 offset:4480
	s_waitcnt lgkmcnt(0)
	v_mfma_f32_16x16x32_bf16 v[38:41], v[30:33], v[42:45], v[38:41]
	ds_read_b128 v[42:45], v149 offset:4544
	s_waitcnt lgkmcnt(0)
	v_mfma_f32_16x16x32_bf16 v[38:41], v[34:37], v[42:45], v[38:41]
	s_nop 7
	ds_write_b32 v150, v38 offset:64
	ds_write_b32 v150, v39 offset:324
	ds_write_b32 v150, v40 offset:584
	ds_write_b32 v150, v41 offset:844
	ds_read_b128 v[38:41], v149 offset:8704
	ds_read_b128 v[42:45], v149 offset:8768
	s_waitcnt lgkmcnt(1)
	v_mfma_f32_16x16x32_bf16 v[38:41], v[2:5], v[38:41], 0
	s_waitcnt lgkmcnt(0)
	v_mfma_f32_16x16x32_bf16 v[38:41], v[26:29], v[42:45], v[38:41]
	ds_read_b128 v[42:45], v149 offset:8832
	s_waitcnt lgkmcnt(0)
	v_mfma_f32_16x16x32_bf16 v[38:41], v[30:33], v[42:45], v[38:41]
	ds_read_b128 v[42:45], v149 offset:8896
	s_waitcnt lgkmcnt(0)
	v_mfma_f32_16x16x32_bf16 v[38:41], v[34:37], v[42:45], v[38:41]
	s_nop 7
	ds_write_b32 v150, v38 offset:128
	ds_write_b32 v150, v39 offset:388
	ds_write_b32 v150, v40 offset:648
	ds_write_b32 v150, v41 offset:908
	ds_read_b128 v[38:41], v149 offset:13056
	s_waitcnt lgkmcnt(0)
	v_mfma_f32_16x16x32_bf16 v[2:5], v[2:5], v[38:41], 0
	ds_read_b128 v[38:41], v149 offset:13120
	s_waitcnt lgkmcnt(0)
	v_mfma_f32_16x16x32_bf16 v[2:5], v[26:29], v[38:41], v[2:5]
	ds_read_b128 v[26:29], v149 offset:13184
	s_waitcnt lgkmcnt(0)
	v_mfma_f32_16x16x32_bf16 v[2:5], v[30:33], v[26:29], v[2:5]
	ds_read_b128 v[26:29], v149 offset:13248
	s_waitcnt lgkmcnt(0)
	v_mfma_f32_16x16x32_bf16 v[2:5], v[34:37], v[26:29], v[2:5]
	s_nop 7
	ds_write_b32 v150, v2 offset:192
	ds_write_b32 v150, v3 offset:452
	ds_write_b32 v150, v4 offset:712
	ds_write_b32 v150, v5 offset:972
	s_waitcnt lgkmcnt(0)
	s_barrier
	ds_read_b32 v2, v121
	ds_read_b32 v3, v122
	v_mov_b32_e32 v4, 0
	v_mov_b32_e32 v5, 0
	s_mov_b64 s[80:81], exec
	v_readlane_b32 s72, v255, 8
	v_readlane_b32 s73, v255, 9
	s_and_b64 s[72:73], s[80:81], s[72:73]
	s_mov_b64 exec, s[72:73]
	s_cbranch_execz .LBB0_581
	ds_read_b32 v5, v123
	ds_read_b32 v6, v95 offset:34816
	s_waitcnt lgkmcnt(1)
	v_sub_f32_e32 v5, v2, v5
	v_mul_f32_e32 v5, 0x3fb8aa3b, v5
	v_exp_f32_e32 v5, v5
	s_waitcnt lgkmcnt(0)
	v_mul_f32_e32 v6, v3, v6
	v_mul_f32_e32 v5, v6, v5

; __device__ __forceinline__ float wave_sum(float v) {
; #pragma unroll
;     for (int o = 1; o < 64; o <<= 1) v += __shfl_xor(v, o);
;     return v;
; __device__ __forceinline__ void ph_final(const P& p, int gw, int ngw, int lane) {
;     for (int m = gw; m < MLAT; m += ngw) {
;         float* row = p.out + (size_t)m * DM;
;         f32x4 v[4]; float ss = 0.f;
; #pragma unroll
;         for (int j = 0; j < 4; ++j) { v[j] = *(const f32x4*)(row + 4 * lane + 256 * j); ss += v[j][0] * v[j][0] + v[j][1] * v[j][1] + v[j][2] * v[j][2] + v[j][3] * v[j][3]; }
;         const float rstd = 1.0f / sqrtf(wave_sum(ss) * (1.f / DM) + EPS);
; #pragma unroll
;         for (int j = 0; j < 4; ++j) { const int col = 4 * lane + 256 * j; const f32x4 gv = *(const f32x4*)(p.fin_g + col); *(f32x4*)(row + col) = v[j] * rstd * gv; }
;     }
.LBB0_976:
	v_mov_b32_e32 v0, 0
	v_readlane_b32 s1, v253, 2
	v_readfirstlane_b32 s0, v146
	s_ashr_i32 s0, s0, 6
	s_add_i32 s2, s0, s1
	v_mov_b32_e32 v3, 0
	s_cmpk_lt_i32 s2, 0x4000
	v_readfirstlane_b32 s0, v0
	s_cbranch_scc0 .LBB0_979
	s_load_dwordx4 s[8:11], s[92:93], s0 offset:0x98
	v_lshlrev_b32_e32 v0, 4, v146
	v_cmp_lt_i32_e32 vcc, v192, v186
	v_and_b32_e32 v2, 0x3f0, v0
	s_ashr_i32 s3, s2, 31
	v_cndmask_b32_e32 v4, v185, v192, vcc
	v_cmp_lt_i32_e32 vcc, v191, v186
	s_waitcnt lgkmcnt(0)
	v_lshl_add_u64 v[0:1], s[8:9], 0, v[2:3]
	s_lshl_b64 s[0:1], s[2:3], 12
	v_cndmask_b32_e32 v2, v185, v191, vcc
	v_cmp_lt_i32_e32 vcc, v190, v186
	v_lshlrev_b32_e32 v5, 2, v2
	s_add_u32 s0, s10, s0
	v_cndmask_b32_e32 v2, v185, v190, vcc
	v_cmp_lt_i32_e32 vcc, v189, v186
	v_lshlrev_b32_e32 v6, 2, v2
	s_addc_u32 s1, s11, s1
	v_cndmask_b32_e32 v2, v185, v189, vcc
	v_cmp_lt_i32_e32 vcc, v188, v186
	v_lshlrev_b32_e32 v7, 2, v2
	v_lshlrev_b32_e32 v4, 2, v4
	v_cndmask_b32_e32 v2, v185, v188, vcc
	v_cmp_lt_i32_e32 vcc, v187, v186
	v_lshlrev_b32_e32 v8, 2, v2
	v_mov_b32_e32 v10, 0x358637bd
	v_cndmask_b32_e32 v2, v185, v187, vcc
	v_lshlrev_b32_e32 v9, 2, v2
	v_and_b32_e32 v2, 63, v146
	v_lshlrev_b32_e32 v2, 4, v2
	v_lshl_add_u64 v[2:3], s[0:1], 0, v[2:3]
	s_mov_b64 s[0:1], 0x800
	v_lshl_add_u64 v[2:3], v[2:3], 0, s[0:1]
	s_mov_b32 s3, 0xf800000
	v_mov_b32_e32 v11, 0x260
	global_load_dwordx4 v[44:47], v[0:1], off
	global_load_dwordx4 v[48:51], v[0:1], off offset:1024
	global_load_dwordx4 v[52:55], v[0:1], off offset:2048
	global_load_dwordx4 v[56:59], v[0:1], off offset:3072
.LBB0_978:
	global_load_dwordx4 v[12:15], v[2:3], off offset:-2048
	global_load_dwordx4 v[16:19], v[2:3], off offset:-1024
	global_load_dwordx4 v[20:23], v[2:3], off
	global_load_dwordx4 v[24:27], v[2:3], off offset:1024
	s_add_i32 s2, s2, s4
	s_cmpk_lt_i32 s2, 0x4000
	s_waitcnt vmcnt(3)
	v_mul_f32_e32 v40, v13, v13
	s_waitcnt vmcnt(2)
	v_mul_f32_e32 v41, v17, v17
	s_waitcnt vmcnt(1)
	v_mov_b32_e32 v34, v21
	s_waitcnt vmcnt(0)
	v_mov_b32_e32 v35, v25
	v_mov_b32_e32 v32, v20
	v_mov_b32_e32 v33, v24
	v_fmac_f32_e32 v40, v12, v12
	v_fmac_f32_e32 v41, v16, v16
	v_pk_mul_f32 v[34:35], v[34:35], v[34:35]
	v_mov_b32_e32 v36, v22
	v_mov_b32_e32 v37, v26
	v_fmac_f32_e32 v40, v14, v14
	v_fmac_f32_e32 v41, v18, v18
	v_pk_fma_f32 v[32:33], v[32:33], v[32:33], v[34:35]
	v_mov_b32_e32 v38, v23
	v_mov_b32_e32 v39, v27
	v_fmac_f32_e32 v40, v15, v15
	v_fmac_f32_e32 v41, v19, v19
	v_pk_fma_f32 v[32:33], v[36:37], v[36:37], v[32:33]
	v_add_f32_e32 v34, v40, v41
	v_pk_fma_f32 v[32:33], v[38:39], v[38:39], v[32:33]
	s_nop 0
	v_add_f32_e32 v32, v34, v32
	v_add_f32_e32 v32, v32, v33
	s_nop 1
	v_add_f32_dpp v32, v32, v32 quad_perm:[1,0,3,2] row_mask:0xf bank_mask:0xf
	s_nop 1
	v_add_f32_dpp v32, v32, v32 quad_perm:[2,3,0,1] row_mask:0xf bank_mask:0xf
	s_nop 1
	v_add_f32_dpp v32, v32, v32 row_half_mirror row_mask:0xf bank_mask:0xf
	s_nop 1
	v_add_f32_dpp v32, v32, v32 row_mirror row_mask:0xf bank_mask:0xf
	s_nop 1
	v_readlane_b32 s12, v32, 0
	v_readlane_b32 s13, v32, 16
	v_readlane_b32 s14, v32, 32
	v_readlane_b32 s15, v32, 48
	s_nop 1
	v_mov_b32_e32 v32, s12
	v_add_f32_e32 v32, s13, v32
	v_add_f32_e32 v32, s14, v32
	v_add_f32_e32 v32, s15, v32
	v_fmamk_f32 v32, v32, 0x3a800000, v10
	v_mul_f32_e32 v33, 0x4f800000, v32
	v_cmp_gt_f32_e32 vcc, s3, v32
	s_nop 1
	v_cndmask_b32_e32 v32, v32, v33, vcc
	v_sqrt_f32_e32 v33, v32
	s_nop 0
	v_add_u32_e32 v34, -1, v33
	v_add_u32_e32 v35, 1, v33
	v_fma_f32 v36, -v34, v33, v32
	v_fma_f32 v37, -v35, v33, v32
	v_cmp_ge_f32_e64 s[0:1], 0, v36
	s_nop 1
	v_cndmask_b32_e64 v33, v33, v34, s[0:1]
	v_cmp_lt_f32_e64 s[0:1], 0, v37
	s_nop 1
	v_cndmask_b32_e64 v33, v33, v35, s[0:1]
	v_mul_f32_e32 v34, 0x37800000, v33
	v_cndmask_b32_e32 v33, v33, v34, vcc
	v_cmp_class_f32_e32 vcc, v32, v11
	s_nop 1
	v_cndmask_b32_e32 v32, v33, v32, vcc
	v_div_scale_f32 v33, s[0:1], v32, v32, 1.0
	v_rcp_f32_e32 v34, v33
	v_div_scale_f32 v35, vcc, 1.0, v32, 1.0
	v_fma_f32 v36, -v33, v34, 1.0
	v_fmac_f32_e32 v34, v36, v34
	v_mul_f32_e32 v36, v35, v34
	v_fma_f32 v37, -v33, v36, v35
	v_fmac_f32_e32 v36, v37, v34
	v_fma_f32 v33, -v33, v36, v35
	v_div_fmas_f32 v33, v33, v34, v36
	v_div_fixup_f32 v32, v33, v32, 1.0
	v_pk_mul_f32 v[12:13], v[12:13], v[32:33] op_sel_hi:[1,0]
	v_pk_mul_f32 v[14:15], v[14:15], v[32:33] op_sel_hi:[1,0]
	v_pk_mul_f32 v[18:19], v[18:19], v[32:33] op_sel_hi:[1,0]
	v_pk_mul_f32 v[16:17], v[16:17], v[32:33] op_sel_hi:[1,0]
	v_pk_mul_f32 v[22:23], v[22:23], v[32:33] op_sel_hi:[1,0]
	v_pk_mul_f32 v[20:21], v[20:21], v[32:33] op_sel_hi:[1,0]
	v_pk_mul_f32 v[26:27], v[26:27], v[32:33] op_sel_hi:[1,0]
	v_pk_mul_f32 v[24:25], v[24:25], v[32:33] op_sel_hi:[1,0]
	v_pk_mul_f32 v[12:13], v[44:45], v[12:13]
	v_pk_mul_f32 v[14:15], v[46:47], v[14:15]
	v_pk_mul_f32 v[18:19], v[50:51], v[18:19]
	v_pk_mul_f32 v[16:17], v[48:49], v[16:17]
	v_pk_mul_f32 v[22:23], v[54:55], v[22:23]
	v_pk_mul_f32 v[20:21], v[52:53], v[20:21]
	v_pk_mul_f32 v[26:27], v[58:59], v[26:27]
	v_pk_mul_f32 v[24:25], v[56:57], v[24:25]
	global_store_dwordx4 v[2:3], v[12:15], off offset:-2048
	global_store_dwordx4 v[2:3], v[16:19], off offset:-1024
	global_store_dwordx4 v[2:3], v[20:23], off
	global_store_dwordx4 v[2:3], v[24:27], off offset:1024
	s_nop 1
	v_lshl_add_u64 v[2:3], v[2:3], 0, s[78:79]
	s_cbranch_scc1 .LBB0_978
